# P0 weight transposes rewritten by hand: one item list over the 8 matrices, next tile's loads in flight, double-buffered LDS with one barrier per tile, 3:1 item split favouring blocks without mod/filt_
# speedup vs baseline: 1.1253x; 1.0033x over previous
.Lwt_fast:
	s_barrier
	v_and_b32_e32 v120, 63, v176
	v_lshrrev_b32_e32 v121, 6, v176
	v_lshlrev_b32_e32 v122, 2, v120
	v_mul_u32_u24_e32 v123, 65, v120
	v_add_lshl_u32 v123, v123, v121, 2
	v_lshrrev_b32_e32 v129, 2, v176
	v_mul_u32_u24_e32 v124, 65, v129
	v_lshlrev_b32_e32 v125, 11, v129
	v_and_b32_e32 v129, 3, v176
	v_lshl_add_u32 v124, v129, 4, v124
	v_lshlrev_b32_e32 v124, 2, v124
	v_lshl_add_u32 v125, v129, 5, v125
	v_add_u32_e32 v127, 0x4100, v123
	v_add_u32_e32 v128, 0x4100, v124
	s_mov_b32 s1, 0
	s_mov_b32 s0, s94
	s_cmpk_lt_u32 s94, 0x150
	s_cbranch_scc1 .Lwt_start
	s_sub_i32 s0, s94, 0x150
	s_mul_i32 s0, s0, 3
	s_addk_i32 s0, 0x150
.Lwt_start:
	s_cmpk_lt_u32 s0, 0x320
	s_cbranch_scc0 .Lwt_p_m1
	s_mov_b32 s2, s0
	v_readlane_b32 s4, v253, 20
	v_readlane_b32 s5, v253, 21
	v_readlane_b32 s6, v252, 20
	v_readlane_b32 s7, v252, 21
	s_movk_i32 s3, 0xc20
	s_mul_i32 s9, s2, 0x51f
	s_lshr_b32 s9, s9, 16
	s_mul_i32 s10, s9, 50
	s_branch .Lwt_p_dec
.Lwt_p_m1:
	s_cmpk_lt_u32 s0, 0x420
	s_cbranch_scc0 .Lwt_p_m2
	s_sub_u32 s2, s0, 0x320
	v_readlane_b32 s4, v253, 28
	v_readlane_b32 s5, v253, 29
	v_readlane_b32 s6, v252, 24
	v_readlane_b32 s7, v252, 25
	s_movk_i32 s3, 0x400
	s_lshr_b32 s9, s2, 4
	s_lshl_b32 s10, s9, 4
	s_branch .Lwt_p_dec
.Lwt_p_m2:
	s_cmpk_lt_u32 s0, 0x620
	s_cbranch_scc0 .Lwt_p_m3
	s_sub_u32 s2, s0, 0x420
	v_readlane_b32 s4, v253, 30
	v_readlane_b32 s5, v253, 31
	v_readlane_b32 s6, v252, 28
	v_readlane_b32 s7, v252, 29
	s_movk_i32 s3, 0x800
	s_lshr_b32 s9, s2, 5
	s_lshl_b32 s10, s9, 5
	s_branch .Lwt_p_dec
.Lwt_p_m3:
	s_cmpk_lt_u32 s0, 0x720
	s_cbranch_scc0 .Lwt_p_m4
	s_sub_u32 s2, s0, 0x620
	v_readlane_b32 s4, v253, 32
	v_readlane_b32 s5, v253, 33
	v_readlane_b32 s6, v252, 30
	v_readlane_b32 s7, v252, 31
	s_movk_i32 s3, 0x400
	s_lshr_b32 s9, s2, 4
	s_lshl_b32 s10, s9, 4
	s_branch .Lwt_p_dec
.Lwt_p_m4:
	s_cmpk_lt_u32 s0, 0xb20
	s_cbranch_scc0 .Lwt_p_m5
	s_sub_u32 s2, s0, 0x720
	v_readlane_b32 s4, v253, 2
	v_readlane_b32 s5, v253, 3
	v_readlane_b32 s6, v252, 32
	v_readlane_b32 s7, v252, 33
	s_movk_i32 s3, 0x1000
	s_lshr_b32 s9, s2, 6
	s_lshl_b32 s10, s9, 6
	s_branch .Lwt_p_dec
.Lwt_p_m5:
	s_cmpk_lt_u32 s0, 0xc20
	s_cbranch_scc0 .Lwt_p_m6
	s_sub_u32 s2, s0, 0xb20
	v_readlane_b32 s4, v252, 58
	v_readlane_b32 s5, v252, 59
	v_readlane_b32 s6, v252, 0
	v_readlane_b32 s7, v252, 1
	s_movk_i32 s3, 0x400
	s_lshr_b32 s9, s2, 4
	s_lshl_b32 s10, s9, 4
	s_branch .Lwt_p_dec
.Lwt_p_m6:
	s_cmpk_lt_u32 s0, 0xf40
	s_cbranch_scc0 .Lwt_p_m7
	s_sub_u32 s2, s0, 0xc20
	v_readlane_b32 s4, v253, 20
	v_readlane_b32 s5, v253, 21
	v_readlane_b32 s6, v252, 22
	v_readlane_b32 s7, v252, 23
	s_add_u32 s4, s4, 0xc20000
	s_addc_u32 s5, s5, 0
	s_movk_i32 s3, 0xc20
	s_mul_i32 s9, s2, 0x51f
	s_lshr_b32 s9, s9, 16
	s_mul_i32 s10, s9, 50
	s_branch .Lwt_p_dec
.Lwt_p_m7:
	s_sub_u32 s2, s0, 0xf40
	v_readlane_b32 s4, v253, 28
	v_readlane_b32 s5, v253, 29
	v_readlane_b32 s6, v252, 26
	v_readlane_b32 s7, v252, 27
	s_add_u32 s4, s4, 0x400000
	s_addc_u32 s5, s5, 0
	s_movk_i32 s3, 0x400
	s_lshr_b32 s9, s2, 4
	s_lshl_b32 s10, s9, 4
	s_branch .Lwt_p_dec
.Lwt_p_dec:
	s_sub_u32 s8, s2, s10
	s_lshl_b32 s8, s8, 6
	s_lshl_b32 s9, s9, 6
	s_mul_i32 s10, s9, s3
	s_lshl_b32 s10, s10, 2
	s_add_u32 s16, s4, s10
	s_addc_u32 s17, s5, 0
	s_lshl_b32 s18, s3, 4
	s_lshl_b32 s10, s8, 10
	s_add_u32 s10, s10, s9
	s_lshl_b32 s10, s10, 1
	s_add_u32 s14, s6, s10
	s_addc_u32 s15, s7, 0
	s_mov_b64 s[12:13], s[14:15]
	v_add_u32_e32 v129, s8, v120
	v_cmp_gt_u32_e64 s[22:23], s3, v129
	s_add_i32 s11, s3, -1
	v_min_u32_e32 v129, s11, v129
	s_lshl_b32 s11, s3, 2
	v_lshlrev_b32_e32 v129, 2, v129
	v_mad_u32_u24 v126, v121, s11, v129
	global_load_dword v130, v126, s[16:17] nt
	s_add_u32 s16, s16, s18
	s_addc_u32 s17, s17, 0
	global_load_dword v131, v126, s[16:17] nt
	s_add_u32 s16, s16, s18
	s_addc_u32 s17, s17, 0
	global_load_dword v132, v126, s[16:17] nt
	s_add_u32 s16, s16, s18
	s_addc_u32 s17, s17, 0
	global_load_dword v133, v126, s[16:17] nt
	s_add_u32 s16, s16, s18
	s_addc_u32 s17, s17, 0
	global_load_dword v134, v126, s[16:17] nt
	s_add_u32 s16, s16, s18
	s_addc_u32 s17, s17, 0
	global_load_dword v135, v126, s[16:17] nt
	s_add_u32 s16, s16, s18
	s_addc_u32 s17, s17, 0
	global_load_dword v136, v126, s[16:17] nt
	s_add_u32 s16, s16, s18
	s_addc_u32 s17, s17, 0
	global_load_dword v137, v126, s[16:17] nt
	s_add_u32 s16, s16, s18
	s_addc_u32 s17, s17, 0
	global_load_dword v138, v126, s[16:17] nt
	s_add_u32 s16, s16, s18
	s_addc_u32 s17, s17, 0
	global_load_dword v139, v126, s[16:17] nt
	s_add_u32 s16, s16, s18
	s_addc_u32 s17, s17, 0
	global_load_dword v140, v126, s[16:17] nt
	s_add_u32 s16, s16, s18
	s_addc_u32 s17, s17, 0
	global_load_dword v141, v126, s[16:17] nt
	s_add_u32 s16, s16, s18
	s_addc_u32 s17, s17, 0
	global_load_dword v142, v126, s[16:17] nt
	s_add_u32 s16, s16, s18
	s_addc_u32 s17, s17, 0
	global_load_dword v143, v126, s[16:17] nt
	s_add_u32 s16, s16, s18
	s_addc_u32 s17, s17, 0
	global_load_dword v144, v126, s[16:17] nt
	s_add_u32 s16, s16, s18
	s_addc_u32 s17, s17, 0
	global_load_dword v145, v126, s[16:17] nt
	s_mov_b32 s19, 1
.Lwt_loop:
	s_cmpk_lt_u32 s94, 0x150
	s_cbranch_scc1 .Lwt_adv_a0
	s_add_i32 s1, s1, 1
	s_cmp_lt_u32 s1, 3
	s_cbranch_scc0 .Lwt_adv_b0
	s_add_i32 s0, s0, 1
	s_branch .Lwt_adv_c0
.Lwt_adv_b0:
	s_mov_b32 s1, 0
	s_addk_i32 s0, 0x35e
	s_branch .Lwt_adv_c0
.Lwt_adv_a0:
	s_addk_i32 s0, 0x360
.Lwt_adv_c0:
	s_cmpk_lt_u32 s0, 0x1040
	s_cbranch_scc0 .Lwt_h0_last
	s_cmpk_lt_u32 s0, 0x320
	s_cbranch_scc0 .Lwt_h0_m1
	s_mov_b32 s2, s0
	v_readlane_b32 s4, v253, 20
	v_readlane_b32 s5, v253, 21
	v_readlane_b32 s6, v252, 20
	v_readlane_b32 s7, v252, 21
	s_movk_i32 s3, 0xc20
	s_mul_i32 s9, s2, 0x51f
	s_lshr_b32 s9, s9, 16
	s_mul_i32 s10, s9, 50
	s_branch .Lwt_h0_dec

.Lwt_h0_dec:
	s_sub_u32 s8, s2, s10
	s_lshl_b32 s8, s8, 6
	s_lshl_b32 s9, s9, 6
	s_mul_i32 s10, s9, s3
	s_lshl_b32 s10, s10, 2
	s_add_u32 s16, s4, s10
	s_addc_u32 s17, s5, 0
	s_lshl_b32 s18, s3, 4
	s_lshl_b32 s10, s8, 10
	s_add_u32 s10, s10, s9
	s_lshl_b32 s10, s10, 1
	s_add_u32 s14, s6, s10
	s_addc_u32 s15, s7, 0
	v_add_u32_e32 v129, s8, v120
	v_cmp_gt_u32_e64 s[26:27], s3, v129
	s_add_i32 s11, s3, -1
	v_min_u32_e32 v129, s11, v129
	s_lshl_b32 s11, s3, 2
	v_lshlrev_b32_e32 v129, 2, v129
	v_mad_u32_u24 v126, v121, s11, v129
	global_load_dword v146, v126, s[16:17] nt
	s_add_u32 s16, s16, s18
	s_addc_u32 s17, s17, 0
	global_load_dword v147, v126, s[16:17] nt
	s_add_u32 s16, s16, s18
	s_addc_u32 s17, s17, 0
	global_load_dword v148, v126, s[16:17] nt
	s_add_u32 s16, s16, s18
	s_addc_u32 s17, s17, 0
	global_load_dword v149, v126, s[16:17] nt
	s_add_u32 s16, s16, s18
	s_addc_u32 s17, s17, 0
	global_load_dword v150, v126, s[16:17] nt
	s_add_u32 s16, s16, s18
	s_addc_u32 s17, s17, 0
	global_load_dword v151, v126, s[16:17] nt
	s_add_u32 s16, s16, s18
	s_addc_u32 s17, s17, 0
	global_load_dword v152, v126, s[16:17] nt
	s_add_u32 s16, s16, s18
	s_addc_u32 s17, s17, 0
	global_load_dword v153, v126, s[16:17] nt
	s_add_u32 s16, s16, s18
	s_addc_u32 s17, s17, 0
	global_load_dword v154, v126, s[16:17] nt
	s_add_u32 s16, s16, s18
	s_addc_u32 s17, s17, 0
	global_load_dword v155, v126, s[16:17] nt
	s_add_u32 s16, s16, s18
	s_addc_u32 s17, s17, 0
	global_load_dword v156, v126, s[16:17] nt
	s_add_u32 s16, s16, s18
	s_addc_u32 s17, s17, 0
	global_load_dword v157, v126, s[16:17] nt
	s_add_u32 s16, s16, s18
	s_addc_u32 s17, s17, 0
	global_load_dword v158, v126, s[16:17] nt
	s_add_u32 s16, s16, s18
	s_addc_u32 s17, s17, 0
	global_load_dword v159, v126, s[16:17] nt
	s_add_u32 s16, s16, s18
	s_addc_u32 s17, s17, 0
	global_load_dword v160, v126, s[16:17] nt
	s_add_u32 s16, s16, s18
	s_addc_u32 s17, s17, 0
	global_load_dword v161, v126, s[16:17] nt
	s_cmp_eq_u32 s19, 0
	s_cbranch_scc1 .Lwt_h0_w18
	s_waitcnt vmcnt(16)
	s_branch .Lwt_h0_go
.Lwt_h0_w18:
	s_waitcnt vmcnt(18)
	s_branch .Lwt_h0_go

.Lwt_h0_go:
	v_cndmask_b32_e64 v130, 0, v130, s[22:23]
	v_cndmask_b32_e64 v131, 0, v131, s[22:23]
	v_cndmask_b32_e64 v132, 0, v132, s[22:23]
	v_cndmask_b32_e64 v133, 0, v133, s[22:23]
	v_cndmask_b32_e64 v134, 0, v134, s[22:23]
	v_cndmask_b32_e64 v135, 0, v135, s[22:23]
	v_cndmask_b32_e64 v136, 0, v136, s[22:23]
	v_cndmask_b32_e64 v137, 0, v137, s[22:23]
	v_cndmask_b32_e64 v138, 0, v138, s[22:23]
	v_cndmask_b32_e64 v139, 0, v139, s[22:23]
	v_cndmask_b32_e64 v140, 0, v140, s[22:23]
	v_cndmask_b32_e64 v141, 0, v141, s[22:23]
	v_cndmask_b32_e64 v142, 0, v142, s[22:23]
	v_cndmask_b32_e64 v143, 0, v143, s[22:23]
	v_cndmask_b32_e64 v144, 0, v144, s[22:23]
	v_cndmask_b32_e64 v145, 0, v145, s[22:23]
	ds_write2_b32 v123, v130, v131 offset0:0 offset1:4
	ds_write2_b32 v123, v132, v133 offset0:8 offset1:12
	ds_write2_b32 v123, v134, v135 offset0:16 offset1:20
	ds_write2_b32 v123, v136, v137 offset0:24 offset1:28
	ds_write2_b32 v123, v138, v139 offset0:32 offset1:36
	ds_write2_b32 v123, v140, v141 offset0:40 offset1:44
	ds_write2_b32 v123, v142, v143 offset0:48 offset1:52
	ds_write2_b32 v123, v144, v145 offset0:56 offset1:60
	s_waitcnt lgkmcnt(0)
	s_barrier
	ds_read2_b32 v[194:195], v124 offset0:0 offset1:1
	ds_read2_b32 v[196:197], v124 offset0:2 offset1:3
	ds_read2_b32 v[198:199], v124 offset0:4 offset1:5
	ds_read2_b32 v[200:201], v124 offset0:6 offset1:7
	ds_read2_b32 v[202:203], v124 offset0:8 offset1:9
	ds_read2_b32 v[204:205], v124 offset0:10 offset1:11
	ds_read2_b32 v[206:207], v124 offset0:12 offset1:13
	ds_read2_b32 v[208:209], v124 offset0:14 offset1:15
	s_waitcnt lgkmcnt(0)
	v_cvt_pk_bf16_f32 v194, v194, v195
	v_cvt_pk_bf16_f32 v195, v196, v197
	v_cvt_pk_bf16_f32 v196, v198, v199
	v_cvt_pk_bf16_f32 v197, v200, v201
	v_cvt_pk_bf16_f32 v198, v202, v203
	v_cvt_pk_bf16_f32 v199, v204, v205
	v_cvt_pk_bf16_f32 v200, v206, v207
	v_cvt_pk_bf16_f32 v201, v208, v209
	global_store_dwordx4 v125, v[194:197], s[12:13]
	global_store_dwordx4 v125, v[198:201], s[12:13] offset:16
	s_mov_b64 s[12:13], s[14:15]
	s_mov_b32 s19, 0
	s_cmpk_lt_u32 s0, 0x1040
	s_cbranch_scc0 .Lwt_done
	s_cmpk_lt_u32 s94, 0x150
	s_cbranch_scc1 .Lwt_adv_a1
	s_add_i32 s1, s1, 1
	s_cmp_lt_u32 s1, 3
	s_cbranch_scc0 .Lwt_adv_b1
	s_add_i32 s0, s0, 1
	s_branch .Lwt_adv_c1

.Lwt_h1_dec:
	s_sub_u32 s8, s2, s10
	s_lshl_b32 s8, s8, 6
	s_lshl_b32 s9, s9, 6
	s_mul_i32 s10, s9, s3
	s_lshl_b32 s10, s10, 2
	s_add_u32 s16, s4, s10
	s_addc_u32 s17, s5, 0
	s_lshl_b32 s18, s3, 4
	s_lshl_b32 s10, s8, 10
	s_add_u32 s10, s10, s9
	s_lshl_b32 s10, s10, 1
	s_add_u32 s14, s6, s10
	s_addc_u32 s15, s7, 0
	v_add_u32_e32 v129, s8, v120
	v_cmp_gt_u32_e64 s[22:23], s3, v129
	s_add_i32 s11, s3, -1
	v_min_u32_e32 v129, s11, v129
	s_lshl_b32 s11, s3, 2
	v_lshlrev_b32_e32 v129, 2, v129
	v_mad_u32_u24 v126, v121, s11, v129
	global_load_dword v130, v126, s[16:17] nt
	s_add_u32 s16, s16, s18
	s_addc_u32 s17, s17, 0
	global_load_dword v131, v126, s[16:17] nt
	s_add_u32 s16, s16, s18
	s_addc_u32 s17, s17, 0
	global_load_dword v132, v126, s[16:17] nt
	s_add_u32 s16, s16, s18
	s_addc_u32 s17, s17, 0
	global_load_dword v133, v126, s[16:17] nt
	s_add_u32 s16, s16, s18
	s_addc_u32 s17, s17, 0
	global_load_dword v134, v126, s[16:17] nt
	s_add_u32 s16, s16, s18
	s_addc_u32 s17, s17, 0
	global_load_dword v135, v126, s[16:17] nt
	s_add_u32 s16, s16, s18
	s_addc_u32 s17, s17, 0
	global_load_dword v136, v126, s[16:17] nt
	s_add_u32 s16, s16, s18
	s_addc_u32 s17, s17, 0
	global_load_dword v137, v126, s[16:17] nt
	s_add_u32 s16, s16, s18
	s_addc_u32 s17, s17, 0
	global_load_dword v138, v126, s[16:17] nt
	s_add_u32 s16, s16, s18
	s_addc_u32 s17, s17, 0
	global_load_dword v139, v126, s[16:17] nt
	s_add_u32 s16, s16, s18
	s_addc_u32 s17, s17, 0
	global_load_dword v140, v126, s[16:17] nt
	s_add_u32 s16, s16, s18
	s_addc_u32 s17, s17, 0
	global_load_dword v141, v126, s[16:17] nt
	s_add_u32 s16, s16, s18
	s_addc_u32 s17, s17, 0
	global_load_dword v142, v126, s[16:17] nt
	s_add_u32 s16, s16, s18
	s_addc_u32 s17, s17, 0
	global_load_dword v143, v126, s[16:17] nt
	s_add_u32 s16, s16, s18
	s_addc_u32 s17, s17, 0
	global_load_dword v144, v126, s[16:17] nt
	s_add_u32 s16, s16, s18
	s_addc_u32 s17, s17, 0
	global_load_dword v145, v126, s[16:17] nt
	s_cmp_eq_u32 s19, 0
	s_cbranch_scc1 .Lwt_h1_w18
	s_waitcnt vmcnt(16)
	s_branch .Lwt_h1_go

.Lwt_h1_go:
	v_cndmask_b32_e64 v146, 0, v146, s[26:27]
	v_cndmask_b32_e64 v147, 0, v147, s[26:27]
	v_cndmask_b32_e64 v148, 0, v148, s[26:27]
	v_cndmask_b32_e64 v149, 0, v149, s[26:27]
	v_cndmask_b32_e64 v150, 0, v150, s[26:27]
	v_cndmask_b32_e64 v151, 0, v151, s[26:27]
	v_cndmask_b32_e64 v152, 0, v152, s[26:27]
	v_cndmask_b32_e64 v153, 0, v153, s[26:27]
	v_cndmask_b32_e64 v154, 0, v154, s[26:27]
	v_cndmask_b32_e64 v155, 0, v155, s[26:27]
	v_cndmask_b32_e64 v156, 0, v156, s[26:27]
	v_cndmask_b32_e64 v157, 0, v157, s[26:27]
	v_cndmask_b32_e64 v158, 0, v158, s[26:27]
	v_cndmask_b32_e64 v159, 0, v159, s[26:27]
	v_cndmask_b32_e64 v160, 0, v160, s[26:27]
	v_cndmask_b32_e64 v161, 0, v161, s[26:27]
	ds_write2_b32 v127, v146, v147 offset0:0 offset1:4
	ds_write2_b32 v127, v148, v149 offset0:8 offset1:12
	ds_write2_b32 v127, v150, v151 offset0:16 offset1:20
	ds_write2_b32 v127, v152, v153 offset0:24 offset1:28
	ds_write2_b32 v127, v154, v155 offset0:32 offset1:36
	ds_write2_b32 v127, v156, v157 offset0:40 offset1:44
	ds_write2_b32 v127, v158, v159 offset0:48 offset1:52
	ds_write2_b32 v127, v160, v161 offset0:56 offset1:60
	s_waitcnt lgkmcnt(0)
	s_barrier
	ds_read2_b32 v[194:195], v128 offset0:0 offset1:1
	ds_read2_b32 v[196:197], v128 offset0:2 offset1:3
	ds_read2_b32 v[198:199], v128 offset0:4 offset1:5
	ds_read2_b32 v[200:201], v128 offset0:6 offset1:7
	ds_read2_b32 v[202:203], v128 offset0:8 offset1:9
	ds_read2_b32 v[204:205], v128 offset0:10 offset1:11
	ds_read2_b32 v[206:207], v128 offset0:12 offset1:13
	ds_read2_b32 v[208:209], v128 offset0:14 offset1:15
	s_waitcnt lgkmcnt(0)
	v_cvt_pk_bf16_f32 v194, v194, v195
	v_cvt_pk_bf16_f32 v195, v196, v197
	v_cvt_pk_bf16_f32 v196, v198, v199
	v_cvt_pk_bf16_f32 v197, v200, v201
	v_cvt_pk_bf16_f32 v198, v202, v203
	v_cvt_pk_bf16_f32 v199, v204, v205
	v_cvt_pk_bf16_f32 v200, v206, v207
	v_cvt_pk_bf16_f32 v201, v208, v209
	global_store_dwordx4 v125, v[194:197], s[12:13]
	global_store_dwordx4 v125, v[198:201], s[12:13] offset:16
	s_mov_b64 s[12:13], s[14:15]
	s_mov_b32 s19, 0
	s_cmpk_lt_u32 s0, 0x1040
	s_cbranch_scc0 .Lwt_done
	s_branch .Lwt_loop
.Lwt_done:
	s_waitcnt vmcnt(0)
	s_branch .LBB0_460
.LBB0_180:
	s_cmpk_eq_i32 s84, 0x200
	s_cbranch_scc1 .Lwt_fast
	v_mov_b32_e32 v4, v176
	s_mov_b32 s0, s94
	s_add_i32 s0, s0, s84
	s_ashr_i32 s1, s0, 31
	s_abs_i32 s0, s0
	s_mul_hi_u32 s2, s0, s50
	s_mul_i32 s2, s2, s49
	s_sub_i32 s0, s0, s2
	s_sub_i32 s2, s0, s49
	s_cmp_ge_u32 s0, s49
	s_cselect_b32 s0, s2, s0
	s_sub_i32 s2, s0, s49
	s_cmp_ge_u32 s0, s49
	s_cselect_b32 s0, s2, s0
	s_xor_b32 s0, s0, s1
	s_sub_i32 s6, s0, s1
	s_cmpk_gt_i32 s6, 0x31f
	s_cbranch_scc1 .LBB0_215
	v_and_b32_e32 v6, 63, v4
	v_readlane_b32 s8, v253, 18
	v_ashrrev_i32_e32 v7, 6, v4
	v_lshlrev_b32_e32 v0, 2, v6
	v_mov_b32_e32 v1, 0
	v_readlane_b32 s10, v253, 20
	v_readlane_b32 s11, v253, 21
	s_movk_i32 s0, 0x104
	v_ashrrev_i32_e32 v9, 2, v4
	v_lshl_add_u64 v[2:3], s[10:11], 0, v[0:1]
	v_lshlrev_b32_e32 v0, 2, v7
	v_mad_u32_u24 v8, v6, s0, v0
	v_lshlrev_b32_e32 v0, 4, v4
	v_readlane_b32 s9, v253, 19
	v_and_b32_e32 v0, 48, v0
	v_mul_lo_u32 v4, v9, s0
	v_lshl_add_u32 v10, v0, 2, v4
	s_lshl_b32 s7, s6, 6
	s_lshl_b32 s8, s84, 6
	s_movk_i32 s9, 0xc20
	s_movk_i32 s10, 0x3080
	v_lshlrev_b32_e32 v0, 1, v0
	v_readlane_b32 s12, v253, 22
	v_readlane_b32 s13, v253, 23
	v_readlane_b32 s14, v253, 24
	v_readlane_b32 s15, v253, 25
	v_readlane_b32 s16, v253, 26
	v_readlane_b32 s17, v253, 27
	v_readlane_b32 s18, v253, 28
	v_readlane_b32 s19, v253, 29
	v_readlane_b32 s20, v253, 30
	v_readlane_b32 s21, v253, 31
	v_readlane_b32 s22, v253, 32
	v_readlane_b32 s23, v253, 33
	s_branch .LBB0_183
